# fused-epilogue residual tile loads issued before the LDS-DMA drain wait and the two re-alignment barriers (counted vmcnt 16)
# speedup vs baseline: 1.0015x; 1.0015x over previous
; __device__ __forceinline__ void panel_rstd(const f32x4 (&v)[2][2][4][2], const Unit& u, int wr, int wc, int fr, int fq, PG8_LAS unsigned char* lds, int wid, int lane,
;                                            float* xslots, unsigned* cnt, unsigned want, float eps) {
;     ...
; #pragma unroll
;     for (int ai = 0; ai < 2; ++ai)
; #pragma unroll
;         for (int m = 0; m < 4; ++m) {
;             float s = 0.f;
; #pragma unroll
;             for (int bj = 0; bj < 2; ++bj)
; #pragma unroll
;                 for (int n = 0; n < 2; ++n) { const f32x4 x = v[ai][bj][m][n]; s += (x[0] * x[0] + x[1] * x[1]) + (x[2] * x[2] + x[3] * x[3]); }
;             s += __shfl_xor(s, 16); s += __shfl_xor(s, 32);
;             if (fq == 0) P[(ai * HALF + wr * 64 + m * 16 + fr) * 4 + wc] = s;
;     __device__ __forceinline__ void fused(f32x4 (&acc)[2][2][4][2], const Unit& u, int wr, int wc, int fr, int fq, PG8_LAS unsigned char* lds, int wid, int lane) const {
;     ...
; #pragma unroll
;         for (int ai = 0; ai < 2; ++ai)
; #pragma unroll
;             for (int m = 0; m < 4; ++m)
; #pragma unroll
;                 for (int bj = 0; bj < 2; ++bj) pre[ai][m][bj] = *(const u32x4v*)(X + (size_t)(u.pm * BM + ai * HALF + wr * 64 + m * 16 + fr) * 1024 + col0 + bj * HALF);
;         panel_rstd(acc, u, wr, wc, fr, fq, lds, wid, lane, xbuf, cnt, want1, 1e-6f);
.LBB0_723:
	s_lshl_b32 s0, s26, 5
	s_lshl_b32 s1, s10, 8
	s_lshl_b32 s40, s39, 8
	v_lshrrev_b32_e32 v0, 1, v206
	s_or_b32 s0, s1, s0
	s_add_i32 s4, s40, s33
	v_and_or_b32 v0, v0, 24, s0
	v_readlane_b32 s12, v255, 3
	v_readlane_b32 s28, v255, 7
	v_readlane_b32 s14, v255, 1
	v_readlane_b32 s30, v255, 5
	v_readlane_b32 s0, v252, 50
	v_or_b32_e32 v100, s4, v219
	v_readlane_b32 s13, v255, 4
	v_readlane_b32 s29, v255, 8
	v_readlane_b32 s15, v255, 2
	v_readlane_b32 s31, v255, 6
	v_readlane_b32 s1, v252, 51
	v_ashrrev_i32_e32 v1, 31, v0
	v_ashrrev_i32_e32 v101, 31, v100
	v_readlane_b32 s22, v253, 6
	v_readlane_b32 s20, v255, 9
	v_readlane_b32 s24, v253, 4
	v_readlane_b32 s18, v255, 11
	v_lshl_add_u64 v[204:205], v[0:1], 1, s[0:1]
	v_lshlrev_b64 v[102:103], 11, v[100:101]
	v_readlane_b32 s23, v253, 7
	v_readlane_b32 s21, v255, 10
	v_readlane_b32 s25, v253, 5
	v_readlane_b32 s41, v255, 36
	v_readlane_b32 s19, v255, 12
	v_lshl_add_u64 v[102:103], v[204:205], 0, v[102:103]
	flat_load_dwordx4 v[192:195], v[102:103]
	flat_load_dwordx4 v[140:143], v[102:103] offset:256
	v_or_b32_e32 v102, 16, v100
	v_ashrrev_i32_e32 v103, 31, v102
	v_lshlrev_b64 v[102:103], 11, v[102:103]
	v_lshl_add_u64 v[102:103], v[204:205], 0, v[102:103]
	flat_load_dwordx4 v[188:191], v[102:103]
	flat_load_dwordx4 v[132:135], v[102:103] offset:256
	v_or_b32_e32 v102, 32, v100
	v_ashrrev_i32_e32 v103, 31, v102
	v_lshlrev_b64 v[102:103], 11, v[102:103]
	v_lshl_add_u64 v[102:103], v[204:205], 0, v[102:103]
	flat_load_dwordx4 v[184:187], v[102:103]
	flat_load_dwordx4 v[128:131], v[102:103] offset:256
	v_or_b32_e32 v102, 48, v100
	v_ashrrev_i32_e32 v103, 31, v102
	v_lshlrev_b64 v[102:103], 11, v[102:103]
	v_lshl_add_u64 v[102:103], v[204:205], 0, v[102:103]
	flat_load_dwordx4 v[180:183], v[102:103]
	flat_load_dwordx4 v[124:127], v[102:103] offset:256
	v_add_u32_e32 v102, 0x80, v100
	v_ashrrev_i32_e32 v103, 31, v102
	v_lshlrev_b64 v[102:103], 11, v[102:103]
	v_lshl_add_u64 v[102:103], v[204:205], 0, v[102:103]
	flat_load_dwordx4 v[176:179], v[102:103]
	flat_load_dwordx4 v[120:123], v[102:103] offset:256
	v_add_u32_e32 v102, 0x90, v100
	v_ashrrev_i32_e32 v103, 31, v102
	v_lshlrev_b64 v[102:103], 11, v[102:103]
	v_lshl_add_u64 v[102:103], v[204:205], 0, v[102:103]
	flat_load_dwordx4 v[172:175], v[102:103]
	flat_load_dwordx4 v[108:111], v[102:103] offset:256
	v_add_u32_e32 v102, 0xa0, v100
	v_add_u32_e32 v100, 0xb0, v100
	v_ashrrev_i32_e32 v103, 31, v102
	v_ashrrev_i32_e32 v101, 31, v100
	v_lshlrev_b64 v[102:103], 11, v[102:103]
	v_lshlrev_b64 v[100:101], 11, v[100:101]
	v_lshl_add_u64 v[102:103], v[204:205], 0, v[102:103]
	v_lshl_add_u64 v[100:101], v[204:205], 0, v[100:101]
	flat_load_dwordx4 v[168:171], v[102:103]
	flat_load_dwordx4 v[104:107], v[102:103] offset:256
	flat_load_dwordx4 v[164:167], v[100:101]
	s_nop 0
	flat_load_dwordx4 v[100:103], v[100:101] offset:256
	s_waitcnt vmcnt(16)
	s_cmpk_gt_u32 s17, 0xff
	s_cbranch_scc1 .LBB0_725
	s_barrier
.LBB0_725:
	s_barrier
	v_mul_f32_e32 v207, v97, v97
	v_mul_f32_e32 v208, v99, v99
	v_fmac_f32_e32 v207, v96, v96
	v_fmac_f32_e32 v208, v98, v98
	v_add_f32_e32 v207, v207, v208
	v_mul_f32_e32 v208, v161, v161
	v_mul_f32_e32 v209, v163, v163
	v_fmac_f32_e32 v208, v160, v160
	v_fmac_f32_e32 v209, v162, v162
	v_add_f32_e32 v208, v208, v209
	v_add_f32_e32 v207, v208, v207
	v_mul_f32_e32 v208, v85, v85
	v_mul_f32_e32 v209, v87, v87
	v_fmac_f32_e32 v208, v84, v84
	v_fmac_f32_e32 v209, v86, v86
	v_add_f32_e32 v208, v208, v209
	v_xor_b32_e32 v2, 16, v225
	v_add_f32_e32 v207, v208, v207
	v_mul_f32_e32 v208, v33, v33
	v_mul_f32_e32 v209, v35, v35
	v_cmp_lt_i32_e32 vcc, v2, v230
	v_fmac_f32_e32 v208, v32, v32
	v_fmac_f32_e32 v209, v34, v34
	v_cndmask_b32_e32 v2, v225, v2, vcc
	v_add_f32_e32 v208, v208, v209
	v_lshlrev_b32_e32 v2, 2, v2
	v_add_f32_e32 v207, v208, v207
	ds_bpermute_b32 v208, v2, v207
	v_xor_b32_e32 v209, 32, v225
	v_cmp_lt_i32_e32 vcc, v209, v230
	s_lshl_b32 s4, s26, 2
	s_add_i32 s48, s4, 0
	v_cndmask_b32_e32 v209, v225, v209, vcc
	v_lshlrev_b32_e32 v221, 2, v209
	s_waitcnt lgkmcnt(0)
	v_add_f32_e32 v207, v207, v208
	ds_bpermute_b32 v209, v221, v207
	v_and_b32_e32 v208, 63, v206
	v_cmp_gt_u32_e64 s[0:1], 16, v208
	s_and_saveexec_b64 s[4:5], s[0:1]
	s_cbranch_execz .LBB0_727
	s_lshl_b32 s6, s38, 10
	s_add_i32 s6, s48, s6
	v_lshl_add_u32 v210, v219, 4, s6
	s_waitcnt lgkmcnt(0)
	v_add_f32_e32 v207, v207, v209
	ds_write_b32 v210, v207
